# retention q|k|v|g GEMM epilogue, v path: the row-rstd loads of row blocks 1-3 are issued with block 0's, so they no longer wait behind each block's 16 scattered 2-byte stores
# baseline (speedup 1.0000x reference)
; __device__ __forceinline__ unsigned f2bf(float f) { unsigned u = __builtin_bit_cast(unsigned, f); return (u + 0x7fffu + ((u >> 16) & 1u)) >> 16; }
; __device__ __forceinline__ float row_rstd(const float* rsp, int t, int n4, int fq) {
;     const f32x4* p = (const f32x4*)(rsp + (size_t)t * 64) + fq * n4; float s = 0.f;
;     for (int i = 0; i < n4; ++i) { const f32x4 v = p[i]; s += (v[0] + v[1]) + (v[2] + v[3]); }
;     s += __shfl_xor(s, 16); s += __shfl_xor(s, 32);
;     return rsqrtf(s * (1.0f / D) + EPS);
; }
;     __device__ __forceinline__ void operator()(const f32x4 (&acc)[2][2][4][2], const pg8::Unit& u, int wr, int wc, int fr, int fq) const {
;     ...
;             const int pv = pn - 16, h = pv >> 1, eb = (pv & 1) * 256 + cl;
; #pragma unroll
;             for (int ai = 0; ai < 2; ++ai)
; #pragma unroll
;                 for (int m = 0; m < 4; ++m) {
;                     const int t = rowb + ai * 128 + m * 16; const float rs = row_rstd(rsp, t, 2, fq);
;                     const int chunk = t >> 6, l = t & 63;
;                     bf16_t* vt = VT + ((size_t)(chunk * 8 + h) * 512 + eb) * 64 + l;
; #pragma unroll
;                     for (int bj = 0; bj < 2; ++bj)
; #pragma unroll
;                         for (int n = 0; n < 2; ++n)
; #pragma unroll
;                             for (int jj = 0; jj < 4; ++jj) vt[(bj * 128 + 4 * n + jj) * 64] = (bf16_t)f2bf(acc[ai][bj][m][n][jj] * rs);
;                 }
.LBB0_554:
	s_andn2_b64 vcc, exec, s[4:5]
	s_cbranch_vccnz .LBB0_556
	v_and_b32_e32 v130, 64, v229
	v_xor_b32_e32 v129, 16, v229
	v_add_u32_e32 v130, 64, v130
	v_cmp_lt_i32_e32 vcc, v129, v130
	s_lshl_b32 s5, s10, 8
	s_and_b32 s5, s5, 0x100
	v_cndmask_b32_e32 v129, v229, v129, vcc
	v_lshlrev_b32_e32 v138, 2, v129
	v_xor_b32_e32 v129, 32, v229
	v_cmp_lt_i32_e32 vcc, v129, v130
	v_or_b32_e32 v128, s5, v154
	v_ashrrev_i32_e32 v169, 31, v168
	v_cndmask_b32_e32 v129, v229, v129, vcc
	v_lshlrev_b32_e32 v139, 2, v129
	v_lshlrev_b32_e32 v192, 7, v128
	v_lshlrev_b64 v[128:129], 8, v[168:169]
	v_lshl_add_u64 v[128:129], v[156:157], 0, v[128:129]
	global_load_dwordx4 v[134:137], v[128:129], off
	global_load_dwordx4 v[140:143], v[128:129], off offset:16
	s_mov_b32 s101, 0
	s_mov_b32 s100, 0x1000
	v_lshl_add_u64 v[240:241], v[128:129], 0, s[100:101]
	global_load_dwordx4 v[198:201], v[240:241], off
	global_load_dwordx4 v[202:205], v[240:241], off offset:16
	s_mov_b32 s100, 0x2000
	v_lshl_add_u64 v[240:241], v[128:129], 0, s[100:101]
	global_load_dwordx4 v[206:209], v[240:241], off
	global_load_dwordx4 v[210:213], v[240:241], off offset:16
	s_mov_b32 s100, 0x3000
	v_lshl_add_u64 v[240:241], v[128:129], 0, s[100:101]
	global_load_dwordx4 v[214:217], v[240:241], off
	global_load_dwordx4 v[236:239], v[240:241], off offset:16
	s_add_i32 s4, s10, -16
	s_lshr_b32 s4, s4, 1
	s_ashr_i32 s5, s11, 3
	s_add_i32 s8, s5, s4
	s_ashr_i32 s9, s8, 31
	v_lshl_add_u64 v[130:131], s[56:57], 0, v[192:193]
	s_lshl_b64 s[8:9], s[8:9], 16
	v_lshl_add_u64 v[132:133], v[130:131], 0, s[8:9]
	v_lshlrev_b32_e32 v192, 1, v152
	v_lshl_add_u64 v[132:133], v[132:133], 0, v[192:193]
	s_movk_i32 s5, 0x4000
	s_waitcnt vmcnt(6)
	v_mov_b32_e32 v170, v134
	v_mov_b32_e32 v171, v140
	v_mov_b32_e32 v140, v135
	v_pk_add_f32 v[134:135], v[170:171], v[140:141]
	v_mov_b32_e32 v140, v136
	v_mov_b32_e32 v141, v142
	v_mov_b32_e32 v142, v137
	v_pk_add_f32 v[136:137], v[140:141], v[142:143]
	s_nop 0
	v_pk_add_f32 v[134:135], v[134:135], v[136:137]
	s_nop 0
	v_add_f32_e32 v134, 0, v134
	v_add_f32_e32 v134, v134, v135
	ds_bpermute_b32 v135, v138, v134
	s_waitcnt lgkmcnt(0)
	v_add_f32_e32 v134, v134, v135
	ds_bpermute_b32 v135, v139, v134
	s_waitcnt lgkmcnt(0)
	v_add_f32_e32 v134, v134, v135
	v_fmamk_f32 v134, v134, 0x3a000000, v223
	v_cmp_gt_f32_e32 vcc, s97, v134
	v_mul_f32_e32 v135, 0x4b800000, v134
	s_nop 0
	v_cndmask_b32_e32 v134, v134, v135, vcc
	v_rsq_f32_e32 v134, v134
	s_nop 0
	v_mul_f32_e32 v135, 0x45800000, v134
	v_cndmask_b32_e32 v136, v134, v135, vcc
	v_mul_f32_e32 v134, v124, v136
	v_bfe_u32 v135, v134, 16, 1
	v_add3_u32 v134, v134, v135, s75
	global_store_short_d16_hi v[132:133], v134, off
	v_mul_f32_e32 v134, v125, v136
	v_bfe_u32 v135, v134, 16, 1
	v_add3_u32 v134, v134, v135, s75
	global_store_short_d16_hi v[132:133], v134, off offset:128
	v_mul_f32_e32 v134, v126, v136
	v_bfe_u32 v135, v134, 16, 1
	v_add3_u32 v134, v134, v135, s75
	global_store_short_d16_hi v[132:133], v134, off offset:256
	v_mul_f32_e32 v134, v127, v136
	v_bfe_u32 v135, v134, 16, 1
	v_add3_u32 v134, v134, v135, s75
	global_store_short_d16_hi v[132:133], v134, off offset:384
	v_mul_f32_e32 v134, v120, v136
	v_bfe_u32 v135, v134, 16, 1
	v_add3_u32 v134, v134, v135, s75
	global_store_short_d16_hi v[132:133], v134, off offset:512
	v_mul_f32_e32 v134, v121, v136
	v_bfe_u32 v135, v134, 16, 1
	v_add3_u32 v134, v134, v135, s75
	global_store_short_d16_hi v[132:133], v134, off offset:640
	v_mul_f32_e32 v134, v122, v136
	v_bfe_u32 v135, v134, 16, 1
	v_add3_u32 v134, v134, v135, s75
	global_store_short_d16_hi v[132:133], v134, off offset:768
	v_mul_f32_e32 v134, v123, v136
	v_bfe_u32 v135, v134, 16, 1
	v_add3_u32 v134, v134, v135, s75
	global_store_short_d16_hi v[132:133], v134, off offset:896
	v_mul_f32_e32 v134, v116, v136
	v_bfe_u32 v135, v134, 16, 1
	v_add3_u32 v137, v134, v135, s75
	v_add_co_u32_e32 v134, vcc, s5, v132
	s_nop 1
	v_addc_co_u32_e32 v135, vcc, 0, v133, vcc
	global_store_short_d16_hi v[134:135], v137, off
	v_mul_f32_e32 v137, v117, v136
	v_bfe_u32 v140, v137, 16, 1
	v_add3_u32 v137, v137, v140, s75
	global_store_short_d16_hi v[134:135], v137, off offset:128
	v_mul_f32_e32 v137, v118, v136
	v_bfe_u32 v140, v137, 16, 1
	v_add3_u32 v137, v137, v140, s75
	global_store_short_d16_hi v[134:135], v137, off offset:256
	v_mul_f32_e32 v137, v119, v136
	v_bfe_u32 v140, v137, 16, 1
	v_add3_u32 v137, v137, v140, s75
	global_store_short_d16_hi v[134:135], v137, off offset:384
	v_mul_f32_e32 v137, v112, v136
	v_bfe_u32 v140, v137, 16, 1
	v_add3_u32 v137, v137, v140, s75
	global_store_short_d16_hi v[134:135], v137, off offset:512
	v_mul_f32_e32 v137, v113, v136
	v_bfe_u32 v140, v137, 16, 1
	v_add3_u32 v137, v137, v140, s75
	global_store_short_d16_hi v[134:135], v137, off offset:640
	v_mul_f32_e32 v137, v114, v136
	v_bfe_u32 v140, v137, 16, 1
	v_add3_u32 v137, v137, v140, s75
	v_mul_f32_e32 v136, v115, v136
	global_store_short_d16_hi v[134:135], v137, off offset:768
	v_bfe_u32 v137, v136, 16, 1
	v_add3_u32 v136, v136, v137, s75
	global_store_short_d16_hi v[134:135], v136, off offset:896
	v_or_b32_e32 v136, 16, v168
	v_ashrrev_i32_e32 v137, 31, v136
	v_lshlrev_b64 v[136:137], 8, v[136:137]
	v_lshl_add_u64 v[136:137], v[156:157], 0, v[136:137]
	s_waitcnt vmcnt(20)
	v_mov_b64_e32 v[140:141], v[198:199]
	v_mov_b64_e32 v[142:143], v[200:201]
	v_mov_b64_e32 v[170:171], v[202:203]
	v_mov_b64_e32 v[172:173], v[204:205]
	v_mov_b32_e32 v136, v140
	v_mov_b32_e32 v137, v170
	v_mov_b32_e32 v170, v141
	v_mov_b32_e32 v140, v142
	v_mov_b32_e32 v141, v172
	v_mov_b32_e32 v172, v143
	v_pk_add_f32 v[136:137], v[136:137], v[170:171]
	v_pk_add_f32 v[140:141], v[140:141], v[172:173]
	s_nop 0
	v_pk_add_f32 v[136:137], v[136:137], v[140:141]
	s_nop 0
	v_add_f32_e32 v136, 0, v136
	v_add_f32_e32 v136, v136, v137
	ds_bpermute_b32 v137, v138, v136
	s_waitcnt lgkmcnt(0)
; __device__ __forceinline__ unsigned f2bf(float f) { unsigned u = __builtin_bit_cast(unsigned, f); return (u + 0x7fffu + ((u >> 16) & 1u)) >> 16; }
; __device__ __forceinline__ float row_rstd(const float* rsp, int t, int n4, int fq) {
;     const f32x4* p = (const f32x4*)(rsp + (size_t)t * 64) + fq * n4; float s = 0.f;
;     for (int i = 0; i < n4; ++i) { const f32x4 v = p[i]; s += (v[0] + v[1]) + (v[2] + v[3]); }
;     s += __shfl_xor(s, 16); s += __shfl_xor(s, 32);
;     return rsqrtf(s * (1.0f / D) + EPS);
; }
;     __device__ __forceinline__ void operator()(const f32x4 (&acc)[2][2][4][2], const pg8::Unit& u, int wr, int wc, int fr, int fq) const {
;     ...
;                 for (int m = 0; m < 4; ++m) {
;                     const int t = rowb + ai * 128 + m * 16; const float rs = row_rstd(rsp, t, 2, fq);
;                     const int chunk = t >> 6, l = t & 63;
;                     bf16_t* vt = VT + ((size_t)(chunk * 8 + h) * 512 + eb) * 64 + l;
; #pragma unroll
;                     for (int bj = 0; bj < 2; ++bj)
; #pragma unroll
;                         for (int n = 0; n < 2; ++n)
; #pragma unroll
;                             for (int jj = 0; jj < 4; ++jj) vt[(bj * 128 + 4 * n + jj) * 64] = (bf16_t)f2bf(acc[ai][bj][m][n][jj] * rs);
;                 }
	v_add_f32_e32 v136, v136, v137
	ds_bpermute_b32 v137, v139, v136
	s_waitcnt lgkmcnt(0)
	v_add_f32_e32 v136, v136, v137
	v_fmamk_f32 v136, v136, 0x3a000000, v223
	v_cmp_gt_f32_e32 vcc, s97, v136
	v_mul_f32_e32 v137, 0x4b800000, v136
	s_nop 0
	v_cndmask_b32_e32 v136, v136, v137, vcc
	v_rsq_f32_e32 v136, v136
	s_nop 0
	v_mul_f32_e32 v137, 0x45800000, v136
	v_cndmask_b32_e32 v136, v136, v137, vcc
	v_mul_f32_e32 v137, v108, v136
	v_bfe_u32 v140, v137, 16, 1
	v_add3_u32 v137, v137, v140, s75
	global_store_short_d16_hi v[132:133], v137, off offset:32
	v_mul_f32_e32 v137, v109, v136
	v_bfe_u32 v140, v137, 16, 1
	v_add3_u32 v137, v137, v140, s75
	global_store_short_d16_hi v[132:133], v137, off offset:160
	v_mul_f32_e32 v137, v110, v136
	v_bfe_u32 v140, v137, 16, 1
	v_add3_u32 v137, v137, v140, s75
	global_store_short_d16_hi v[132:133], v137, off offset:288
	v_mul_f32_e32 v137, v111, v136
	v_bfe_u32 v140, v137, 16, 1
	v_add3_u32 v137, v137, v140, s75
	global_store_short_d16_hi v[132:133], v137, off offset:416
	v_mul_f32_e32 v137, v104, v136
	v_bfe_u32 v140, v137, 16, 1
	v_add3_u32 v137, v137, v140, s75
	global_store_short_d16_hi v[132:133], v137, off offset:544
	v_mul_f32_e32 v137, v105, v136
	v_bfe_u32 v140, v137, 16, 1
	v_add3_u32 v137, v137, v140, s75
	global_store_short_d16_hi v[132:133], v137, off offset:672
	v_mul_f32_e32 v137, v106, v136
	v_bfe_u32 v140, v137, 16, 1
	v_add3_u32 v137, v137, v140, s75
	global_store_short_d16_hi v[132:133], v137, off offset:800
	v_mul_f32_e32 v137, v107, v136
	v_bfe_u32 v140, v137, 16, 1
	v_add3_u32 v137, v137, v140, s75
	global_store_short_d16_hi v[132:133], v137, off offset:928
	v_mul_f32_e32 v137, v100, v136
	v_bfe_u32 v140, v137, 16, 1
	v_add3_u32 v137, v137, v140, s75
	global_store_short_d16_hi v[134:135], v137, off offset:32
	v_mul_f32_e32 v137, v101, v136
	v_bfe_u32 v140, v137, 16, 1
	v_add3_u32 v137, v137, v140, s75
	global_store_short_d16_hi v[134:135], v137, off offset:160
	v_mul_f32_e32 v137, v102, v136
	v_bfe_u32 v140, v137, 16, 1
	v_add3_u32 v137, v137, v140, s75
	global_store_short_d16_hi v[134:135], v137, off offset:288
	v_mul_f32_e32 v137, v103, v136
	v_bfe_u32 v140, v137, 16, 1
	v_add3_u32 v137, v137, v140, s75
	global_store_short_d16_hi v[134:135], v137, off offset:416
	v_mul_f32_e32 v137, v96, v136
	v_bfe_u32 v140, v137, 16, 1
	v_add3_u32 v137, v137, v140, s75
	global_store_short_d16_hi v[134:135], v137, off offset:544
	v_mul_f32_e32 v137, v97, v136
	v_bfe_u32 v140, v137, 16, 1
	v_add3_u32 v137, v137, v140, s75
	global_store_short_d16_hi v[134:135], v137, off offset:672
	v_mul_f32_e32 v137, v98, v136
	v_bfe_u32 v140, v137, 16, 1
	v_add3_u32 v137, v137, v140, s75
	v_mul_f32_e32 v136, v99, v136
	global_store_short_d16_hi v[134:135], v137, off offset:800
	v_bfe_u32 v137, v136, 16, 1
	v_add3_u32 v136, v136, v137, s75
	global_store_short_d16_hi v[134:135], v136, off offset:928
	v_or_b32_e32 v136, 32, v168
	v_ashrrev_i32_e32 v137, 31, v136
	v_lshlrev_b64 v[136:137], 8, v[136:137]
	v_lshl_add_u64 v[136:137], v[156:157], 0, v[136:137]
	s_waitcnt vmcnt(34)
	v_mov_b64_e32 v[140:141], v[206:207]
	v_mov_b64_e32 v[142:143], v[208:209]
	v_mov_b64_e32 v[170:171], v[210:211]
	v_mov_b64_e32 v[172:173], v[212:213]
	v_mov_b32_e32 v136, v140
	v_mov_b32_e32 v137, v170
	v_mov_b32_e32 v170, v141
	v_mov_b32_e32 v140, v142
	v_mov_b32_e32 v141, v172
	v_mov_b32_e32 v172, v143
	v_pk_add_f32 v[136:137], v[136:137], v[170:171]
	v_pk_add_f32 v[140:141], v[140:141], v[172:173]
	s_nop 0
	v_pk_add_f32 v[136:137], v[136:137], v[140:141]
	s_nop 0
	v_add_f32_e32 v136, 0, v136
	v_add_f32_e32 v136, v136, v137
	ds_bpermute_b32 v137, v138, v136
	s_waitcnt lgkmcnt(0)
	v_add_f32_e32 v136, v136, v137
	ds_bpermute_b32 v137, v139, v136
	s_waitcnt lgkmcnt(0)
	v_add_f32_e32 v136, v136, v137
	v_fmamk_f32 v136, v136, 0x3a000000, v223
	v_cmp_gt_f32_e32 vcc, s97, v136
	v_mul_f32_e32 v137, 0x4b800000, v136
	s_nop 0
	v_cndmask_b32_e32 v136, v136, v137, vcc
	v_rsq_f32_e32 v136, v136
	s_nop 0
	v_mul_f32_e32 v137, 0x45800000, v136
	v_cndmask_b32_e32 v136, v136, v137, vcc
	v_mul_f32_e32 v137, v92, v136
	v_bfe_u32 v140, v137, 16, 1
	v_add3_u32 v137, v137, v140, s75
	global_store_short_d16_hi v[132:133], v137, off offset:64
	v_mul_f32_e32 v137, v93, v136
	v_bfe_u32 v140, v137, 16, 1
	v_add3_u32 v137, v137, v140, s75
	global_store_short_d16_hi v[132:133], v137, off offset:192
	v_mul_f32_e32 v137, v94, v136
	v_bfe_u32 v140, v137, 16, 1
	v_add3_u32 v137, v137, v140, s75
	global_store_short_d16_hi v[132:133], v137, off offset:320
	v_mul_f32_e32 v137, v95, v136
	v_bfe_u32 v140, v137, 16, 1
	v_add3_u32 v137, v137, v140, s75
	global_store_short_d16_hi v[132:133], v137, off offset:448
	v_mul_f32_e32 v137, v88, v136
	v_bfe_u32 v140, v137, 16, 1
	v_add3_u32 v137, v137, v140, s75
	global_store_short_d16_hi v[132:133], v137, off offset:576
	v_mul_f32_e32 v137, v89, v136
	v_bfe_u32 v140, v137, 16, 1
	v_add3_u32 v137, v137, v140, s75
	global_store_short_d16_hi v[132:133], v137, off offset:704
	v_mul_f32_e32 v137, v90, v136
	v_bfe_u32 v140, v137, 16, 1
	v_add3_u32 v137, v137, v140, s75
	global_store_short_d16_hi v[132:133], v137, off offset:832
	v_mul_f32_e32 v137, v91, v136
	v_bfe_u32 v140, v137, 16, 1
	v_add3_u32 v137, v137, v140, s75
	global_store_short_d16_hi v[132:133], v137, off offset:960
	v_mul_f32_e32 v137, v84, v136
	v_bfe_u32 v140, v137, 16, 1
	v_add3_u32 v137, v137, v140, s75
	global_store_short_d16_hi v[134:135], v137, off offset:64
	v_mul_f32_e32 v137, v85, v136
	v_bfe_u32 v140, v137, 16, 1
	v_add3_u32 v137, v137, v140, s75
	global_store_short_d16_hi v[134:135], v137, off offset:192
	v_mul_f32_e32 v137, v86, v136
	v_bfe_u32 v140, v137, 16, 1
	v_add3_u32 v137, v137, v140, s75
	global_store_short_d16_hi v[134:135], v137, off offset:320
	v_mul_f32_e32 v137, v87, v136
	v_bfe_u32 v140, v137, 16, 1
	v_add3_u32 v137, v137, v140, s75
	global_store_short_d16_hi v[134:135], v137, off offset:448
	v_mul_f32_e32 v137, v80, v136
	v_bfe_u32 v140, v137, 16, 1
	v_add3_u32 v137, v137, v140, s75
	global_store_short_d16_hi v[134:135], v137, off offset:576
	v_mul_f32_e32 v137, v81, v136
	v_bfe_u32 v140, v137, 16, 1
	v_add3_u32 v137, v137, v140, s75
	global_store_short_d16_hi v[134:135], v137, off offset:704
	v_mul_f32_e32 v137, v82, v136
	v_bfe_u32 v140, v137, 16, 1
	v_add3_u32 v137, v137, v140, s75
	v_mul_f32_e32 v136, v83, v136
	global_store_short_d16_hi v[134:135], v137, off offset:832
	v_bfe_u32 v137, v136, 16, 1
	v_add3_u32 v136, v136, v137, s75
	global_store_short_d16_hi v[134:135], v136, off offset:960
	v_or_b32_e32 v136, 48, v168
	v_ashrrev_i32_e32 v137, 31, v136
	v_lshlrev_b64 v[136:137], 8, v[136:137]
	v_lshl_add_u64 v[136:137], v[156:157], 0, v[136:137]
	s_waitcnt vmcnt(48)
; __device__ __forceinline__ unsigned f2bf(float f) { unsigned u = __builtin_bit_cast(unsigned, f); return (u + 0x7fffu + ((u >> 16) & 1u)) >> 16; }
; __device__ __forceinline__ float row_rstd(const float* rsp, int t, int n4, int fq) {
;     const f32x4* p = (const f32x4*)(rsp + (size_t)t * 64) + fq * n4; float s = 0.f;
;     for (int i = 0; i < n4; ++i) { const f32x4 v = p[i]; s += (v[0] + v[1]) + (v[2] + v[3]); }
;     s += __shfl_xor(s, 16); s += __shfl_xor(s, 32);
;     return rsqrtf(s * (1.0f / D) + EPS);
; }
;     __device__ __forceinline__ void operator()(const f32x4 (&acc)[2][2][4][2], const pg8::Unit& u, int wr, int wc, int fr, int fq) const {
;     ...
;                 for (int m = 0; m < 4; ++m) {
;                     const int t = rowb + ai * 128 + m * 16; const float rs = row_rstd(rsp, t, 2, fq);
;                     const int chunk = t >> 6, l = t & 63;
;                     bf16_t* vt = VT + ((size_t)(chunk * 8 + h) * 512 + eb) * 64 + l;
; #pragma unroll
;                     for (int bj = 0; bj < 2; ++bj)
; #pragma unroll
;                         for (int n = 0; n < 2; ++n)
; #pragma unroll
;                             for (int jj = 0; jj < 4; ++jj) vt[(bj * 128 + 4 * n + jj) * 64] = (bf16_t)f2bf(acc[ai][bj][m][n][jj] * rs);
;                 }
	v_mov_b64_e32 v[140:141], v[214:215]
	v_mov_b64_e32 v[142:143], v[216:217]
	v_mov_b64_e32 v[170:171], v[236:237]
	v_mov_b64_e32 v[172:173], v[238:239]
	v_mov_b32_e32 v136, v140
	v_mov_b32_e32 v137, v170
	v_mov_b32_e32 v170, v141
	v_mov_b32_e32 v140, v142
	v_mov_b32_e32 v141, v172
	v_mov_b32_e32 v172, v143
	v_pk_add_f32 v[136:137], v[136:137], v[170:171]
	v_pk_add_f32 v[140:141], v[140:141], v[172:173]
	s_nop 0
	v_pk_add_f32 v[136:137], v[136:137], v[140:141]
	s_nop 0
	v_add_f32_e32 v136, 0, v136
	v_add_f32_e32 v136, v136, v137
	ds_bpermute_b32 v137, v138, v136
	s_waitcnt lgkmcnt(0)
	v_add_f32_e32 v136, v136, v137
	ds_bpermute_b32 v137, v139, v136
	s_waitcnt lgkmcnt(0)
	v_add_f32_e32 v136, v136, v137
	v_fmamk_f32 v136, v136, 0x3a000000, v223
	v_cmp_gt_f32_e32 vcc, s97, v136
	v_mul_f32_e32 v137, 0x4b800000, v136
	s_nop 0
	v_cndmask_b32_e32 v136, v136, v137, vcc
	v_rsq_f32_e32 v136, v136
	s_nop 0
	v_mul_f32_e32 v137, 0x45800000, v136
	v_cndmask_b32_e32 v136, v136, v137, vcc
	v_mul_f32_e32 v137, v76, v136
	v_bfe_u32 v140, v137, 16, 1
	v_add3_u32 v137, v137, v140, s75
	global_store_short_d16_hi v[132:133], v137, off offset:96
	v_mul_f32_e32 v137, v77, v136
	v_bfe_u32 v140, v137, 16, 1
	v_add3_u32 v137, v137, v140, s75
	global_store_short_d16_hi v[132:133], v137, off offset:224
	v_mul_f32_e32 v137, v78, v136
	v_bfe_u32 v140, v137, 16, 1
	v_add3_u32 v137, v137, v140, s75
	global_store_short_d16_hi v[132:133], v137, off offset:352
	v_mul_f32_e32 v137, v79, v136
	v_bfe_u32 v140, v137, 16, 1
	v_add3_u32 v137, v137, v140, s75
	global_store_short_d16_hi v[132:133], v137, off offset:480
	v_mul_f32_e32 v137, v72, v136
	v_bfe_u32 v140, v137, 16, 1
	v_add3_u32 v137, v137, v140, s75
	global_store_short_d16_hi v[132:133], v137, off offset:608
	v_mul_f32_e32 v137, v73, v136
	v_bfe_u32 v140, v137, 16, 1
	v_add3_u32 v137, v137, v140, s75
	global_store_short_d16_hi v[132:133], v137, off offset:736
	v_mul_f32_e32 v137, v74, v136
	v_bfe_u32 v140, v137, 16, 1
	v_add3_u32 v137, v137, v140, s75
	global_store_short_d16_hi v[132:133], v137, off offset:864
	v_mul_f32_e32 v137, v75, v136
	v_bfe_u32 v140, v137, 16, 1
	v_add3_u32 v137, v137, v140, s75
	global_store_short_d16_hi v[132:133], v137, off offset:992
	v_mul_f32_e32 v132, v68, v136
	v_bfe_u32 v133, v132, 16, 1
	v_add3_u32 v132, v132, v133, s75
	global_store_short_d16_hi v[134:135], v132, off offset:96
	v_mul_f32_e32 v132, v69, v136
	v_bfe_u32 v133, v132, 16, 1
	v_add3_u32 v132, v132, v133, s75
	global_store_short_d16_hi v[134:135], v132, off offset:224
	v_mul_f32_e32 v132, v70, v136
	v_bfe_u32 v133, v132, 16, 1
	v_add3_u32 v132, v132, v133, s75
	global_store_short_d16_hi v[134:135], v132, off offset:352
	v_mul_f32_e32 v132, v71, v136
	v_bfe_u32 v133, v132, 16, 1
	v_add3_u32 v132, v132, v133, s75
	global_store_short_d16_hi v[134:135], v132, off offset:480
	v_mul_f32_e32 v132, v64, v136
	v_bfe_u32 v133, v132, 16, 1
	v_add3_u32 v132, v132, v133, s75
	global_store_short_d16_hi v[134:135], v132, off offset:608
	v_mul_f32_e32 v132, v65, v136
	v_bfe_u32 v133, v132, 16, 1
	v_add3_u32 v132, v132, v133, s75
	global_store_short_d16_hi v[134:135], v132, off offset:736
	v_mul_f32_e32 v132, v66, v136
	v_bfe_u32 v133, v132, 16, 1
	v_add3_u32 v132, v132, v133, s75
	global_store_short_d16_hi v[134:135], v132, off offset:864
	v_mul_f32_e32 v132, v67, v136
	v_bfe_u32 v133, v132, 16, 1
	v_add3_u32 v132, v132, v133, s75
	global_store_short_d16_hi v[134:135], v132, off offset:992
	v_add_u32_e32 v132, 0x80, v168
	v_ashrrev_i32_e32 v133, 3, v132
	v_and_b32_e32 v133, -8, v133
	v_add_u32_e32 v134, s4, v133
	v_ashrrev_i32_e32 v133, 31, v132
	v_ashrrev_i32_e32 v135, 31, v134
	v_lshlrev_b64 v[132:133], 8, v[132:133]
	v_lshlrev_b64 v[134:135], 16, v[134:135]
	v_lshl_add_u64 v[132:133], v[156:157], 0, v[132:133]
	v_lshl_add_u64 v[130:131], v[130:131], 0, v[134:135]
	global_load_dwordx4 v[134:137], v[132:133], off
	global_load_dwordx4 v[140:143], v[132:133], off offset:16
	s_waitcnt vmcnt(1)
	v_mov_b32_e32 v132, v134
	s_waitcnt vmcnt(0)
	v_mov_b32_e32 v133, v140
	v_mov_b32_e32 v140, v135
	v_mov_b32_e32 v134, v136
	v_mov_b32_e32 v135, v142
	v_mov_b32_e32 v142, v137
	v_pk_add_f32 v[132:133], v[132:133], v[140:141]
	v_pk_add_f32 v[134:135], v[134:135], v[142:143]
	s_nop 0
	v_pk_add_f32 v[132:133], v[132:133], v[134:135]
	s_nop 0
	v_add_f32_e32 v132, 0, v132
	v_add_f32_e32 v132, v132, v133
	ds_bpermute_b32 v133, v138, v132
	s_waitcnt lgkmcnt(0)
	v_add_f32_e32 v132, v132, v133
	ds_bpermute_b32 v133, v139, v132
	s_waitcnt lgkmcnt(0)
; __device__ __forceinline__ unsigned f2bf(float f) { unsigned u = __builtin_bit_cast(unsigned, f); return (u + 0x7fffu + ((u >> 16) & 1u)) >> 16; }
; __device__ __forceinline__ float row_rstd(const float* rsp, int t, int n4, int fq) {
;     const f32x4* p = (const f32x4*)(rsp + (size_t)t * 64) + fq * n4; float s = 0.f;
;     for (int i = 0; i < n4; ++i) { const f32x4 v = p[i]; s += (v[0] + v[1]) + (v[2] + v[3]); }
;     s += __shfl_xor(s, 16); s += __shfl_xor(s, 32);
;     return rsqrtf(s * (1.0f / D) + EPS);
; }
;     __device__ __forceinline__ void operator()(const f32x4 (&acc)[2][2][4][2], const pg8::Unit& u, int wr, int wc, int fr, int fq) const {
;     ...
;                     const int t = rowb + ai * 128 + m * 16; const float rs = row_rstd(rsp, t, 2, fq);
;                     const int chunk = t >> 6, l = t & 63;
;                     bf16_t* vt = VT + ((size_t)(chunk * 8 + h) * 512 + eb) * 64 + l;
; #pragma unroll
;                     for (int bj = 0; bj < 2; ++bj)
; #pragma unroll
;                         for (int n = 0; n < 2; ++n)
; #pragma unroll
;                             for (int jj = 0; jj < 4; ++jj) vt[(bj * 128 + 4 * n + jj) * 64] = (bf16_t)f2bf(acc[ai][bj][m][n][jj] * rs);
	v_add_f32_e32 v132, v132, v133
	v_fmamk_f32 v132, v132, 0x3a000000, v223
	v_cmp_gt_f32_e32 vcc, s97, v132
	v_mul_f32_e32 v133, 0x4b800000, v132
	s_nop 0
	v_cndmask_b32_e32 v132, v132, v133, vcc
	v_rsq_f32_e32 v132, v132
	s_nop 0
	v_mul_f32_e32 v133, 0x45800000, v132
	v_cndmask_b32_e32 v134, v132, v133, vcc
	v_lshl_add_u64 v[132:133], v[130:131], 0, v[192:193]
	v_mul_f32_e32 v130, v60, v134
	v_bfe_u32 v131, v130, 16, 1
	v_add3_u32 v130, v130, v131, s75
	global_store_short_d16_hi v[132:133], v130, off
	v_mul_f32_e32 v130, v61, v134
	v_bfe_u32 v131, v130, 16, 1
	v_add3_u32 v130, v130, v131, s75
	global_store_short_d16_hi v[132:133], v130, off offset:128
	v_mul_f32_e32 v130, v62, v134
	v_bfe_u32 v131, v130, 16, 1
	v_add3_u32 v130, v130, v131, s75
	global_store_short_d16_hi v[132:133], v130, off offset:256
	v_mul_f32_e32 v130, v63, v134
	v_bfe_u32 v131, v130, 16, 1
	v_add3_u32 v130, v130, v131, s75
	global_store_short_d16_hi v[132:133], v130, off offset:384
	v_mul_f32_e32 v130, v56, v134
	v_bfe_u32 v131, v130, 16, 1
	v_add3_u32 v130, v130, v131, s75
	global_store_short_d16_hi v[132:133], v130, off offset:512
	v_mul_f32_e32 v130, v57, v134
	v_bfe_u32 v131, v130, 16, 1
	v_add3_u32 v130, v130, v131, s75
	global_store_short_d16_hi v[132:133], v130, off offset:640
	v_mul_f32_e32 v130, v58, v134
	v_bfe_u32 v131, v130, 16, 1
	v_add3_u32 v130, v130, v131, s75
	global_store_short_d16_hi v[132:133], v130, off offset:768
	v_mul_f32_e32 v130, v59, v134
	v_bfe_u32 v131, v130, 16, 1
	v_add3_u32 v130, v130, v131, s75
	global_store_short_d16_hi v[132:133], v130, off offset:896
	v_mul_f32_e32 v130, v52, v134
	v_bfe_u32 v131, v130, 16, 1
	v_add3_u32 v135, v130, v131, s75
	v_add_co_u32_e32 v130, vcc, s5, v132
	s_mov_b64 s[4:5], 0x9000
	s_nop 0
	v_addc_co_u32_e32 v131, vcc, 0, v133, vcc
	global_store_short_d16_hi v[130:131], v135, off
	v_mul_f32_e32 v135, v53, v134
	v_bfe_u32 v136, v135, 16, 1
	v_add3_u32 v135, v135, v136, s75
	global_store_short_d16_hi v[130:131], v135, off offset:128
	v_mul_f32_e32 v135, v54, v134
	v_bfe_u32 v136, v135, 16, 1
	v_add3_u32 v135, v135, v136, s75
	global_store_short_d16_hi v[130:131], v135, off offset:256
	v_mul_f32_e32 v135, v55, v134
	v_bfe_u32 v136, v135, 16, 1
	v_add3_u32 v135, v135, v136, s75
	global_store_short_d16_hi v[130:131], v135, off offset:384
	v_mul_f32_e32 v135, v48, v134
	v_bfe_u32 v136, v135, 16, 1
	v_add3_u32 v135, v135, v136, s75
	global_store_short_d16_hi v[130:131], v135, off offset:512
	v_mul_f32_e32 v135, v49, v134
	v_bfe_u32 v136, v135, 16, 1
	v_add3_u32 v135, v135, v136, s75
	global_store_short_d16_hi v[130:131], v135, off offset:640
	v_mul_f32_e32 v135, v50, v134
	v_bfe_u32 v136, v135, 16, 1
	v_add3_u32 v135, v135, v136, s75
	v_mul_f32_e32 v134, v51, v134
	global_store_short_d16_hi v[130:131], v135, off offset:768
	v_bfe_u32 v135, v134, 16, 1
	v_add3_u32 v134, v134, v135, s75
	v_lshl_add_u64 v[136:137], v[128:129], 0, s[4:5]
	s_mov_b32 s4, 0xa000
	global_store_short_d16_hi v[130:131], v134, off offset:896
	v_add_co_u32_e32 v134, vcc, s4, v128
	s_mov_b64 s[4:5], 0xa000
	s_nop 0
	v_addc_co_u32_e32 v135, vcc, 0, v129, vcc
	global_load_dwordx4 v[140:143], v[134:135], off offset:-4096
	global_load_dwordx4 v[170:173], v[136:137], off offset:16
	s_waitcnt vmcnt(1)
	v_mov_b32_e32 v136, v140
	s_waitcnt vmcnt(0)
	v_mov_b32_e32 v137, v170
	v_mov_b32_e32 v170, v141
	v_mov_b32_e32 v140, v142
	v_mov_b32_e32 v141, v172
	v_mov_b32_e32 v172, v143
	v_pk_add_f32 v[136:137], v[136:137], v[170:171]
	v_pk_add_f32 v[140:141], v[140:141], v[172:173]
	s_nop 0
	v_pk_add_f32 v[136:137], v[136:137], v[140:141]
	s_nop 0
	v_add_f32_e32 v136, 0, v136
	v_add_f32_e32 v136, v136, v137
	ds_bpermute_b32 v137, v138, v136
	s_waitcnt lgkmcnt(0)
	v_add_f32_e32 v136, v136, v137
	ds_bpermute_b32 v137, v139, v136
	s_waitcnt lgkmcnt(0)
	v_add_f32_e32 v136, v136, v137
	v_fmamk_f32 v136, v136, 0x3a000000, v223
	v_cmp_gt_f32_e32 vcc, s97, v136
	v_mul_f32_e32 v137, 0x4b800000, v136
	s_nop 0
	v_cndmask_b32_e32 v136, v136, v137, vcc
	v_rsq_f32_e32 v136, v136
	s_nop 0
	v_mul_f32_e32 v137, 0x45800000, v136
	v_cndmask_b32_e32 v136, v136, v137, vcc
	v_mul_f32_e32 v137, v44, v136
	v_bfe_u32 v140, v137, 16, 1
	v_add3_u32 v137, v137, v140, s75
	global_store_short_d16_hi v[132:133], v137, off offset:32
	v_mul_f32_e32 v137, v45, v136
	v_bfe_u32 v140, v137, 16, 1
	v_add3_u32 v137, v137, v140, s75
	global_store_short_d16_hi v[132:133], v137, off offset:160
	v_mul_f32_e32 v137, v46, v136
	v_bfe_u32 v140, v137, 16, 1
	v_add3_u32 v137, v137, v140, s75
	global_store_short_d16_hi v[132:133], v137, off offset:288
	v_mul_f32_e32 v137, v47, v136
	v_bfe_u32 v140, v137, 16, 1
	v_add3_u32 v137, v137, v140, s75
	global_store_short_d16_hi v[132:133], v137, off offset:416
	v_mul_f32_e32 v137, v40, v136
	v_bfe_u32 v140, v137, 16, 1
	v_add3_u32 v137, v137, v140, s75
	global_store_short_d16_hi v[132:133], v137, off offset:544
	v_mul_f32_e32 v137, v41, v136
	v_bfe_u32 v140, v137, 16, 1
	v_add3_u32 v137, v137, v140, s75
	global_store_short_d16_hi v[132:133], v137, off offset:672
	v_mul_f32_e32 v137, v42, v136
	v_bfe_u32 v140, v137, 16, 1
	v_add3_u32 v137, v137, v140, s75
	global_store_short_d16_hi v[132:133], v137, off offset:800
	v_mul_f32_e32 v137, v43, v136
	v_bfe_u32 v140, v137, 16, 1
	v_add3_u32 v137, v137, v140, s75
	global_store_short_d16_hi v[132:133], v137, off offset:928
	v_mul_f32_e32 v137, v36, v136
	v_bfe_u32 v140, v137, 16, 1
	v_add3_u32 v137, v137, v140, s75
	global_store_short_d16_hi v[130:131], v137, off offset:32
	v_mul_f32_e32 v137, v37, v136
	v_bfe_u32 v140, v137, 16, 1
	v_add3_u32 v137, v137, v140, s75
	global_store_short_d16_hi v[130:131], v137, off offset:160
	v_mul_f32_e32 v137, v38, v136
	v_bfe_u32 v140, v137, 16, 1
	v_add3_u32 v137, v137, v140, s75
	global_store_short_d16_hi v[130:131], v137, off offset:288
	v_mul_f32_e32 v137, v39, v136
	v_bfe_u32 v140, v137, 16, 1
	v_add3_u32 v137, v137, v140, s75
	global_store_short_d16_hi v[130:131], v137, off offset:416
	v_mul_f32_e32 v137, v32, v136
	v_bfe_u32 v140, v137, 16, 1
	v_add3_u32 v137, v137, v140, s75
	global_store_short_d16_hi v[130:131], v137, off offset:544
	v_mul_f32_e32 v137, v33, v136
	v_bfe_u32 v140, v137, 16, 1
	v_add3_u32 v137, v137, v140, s75
	global_store_short_d16_hi v[130:131], v137, off offset:672
	v_mul_f32_e32 v137, v34, v136
	v_bfe_u32 v140, v137, 16, 1
	v_add3_u32 v137, v137, v140, s75
	v_mul_f32_e32 v136, v35, v136
	global_store_short_d16_hi v[130:131], v137, off offset:800
	v_bfe_u32 v137, v136, 16, 1
	v_add3_u32 v136, v136, v137, s75
	global_store_short_d16_hi v[130:131], v136, off offset:928
	v_lshl_add_u64 v[136:137], v[128:129], 0, s[4:5]
	global_load_dwordx4 v[140:143], v[134:135], off
	s_nop 0
	global_load_dwordx4 v[134:137], v[136:137], off offset:16
	s_mov_b64 s[4:5], 0xb000
	s_waitcnt vmcnt(1)
; __device__ __forceinline__ unsigned f2bf(float f) { unsigned u = __builtin_bit_cast(unsigned, f); return (u + 0x7fffu + ((u >> 16) & 1u)) >> 16; }
; __device__ __forceinline__ float row_rstd(const float* rsp, int t, int n4, int fq) {
;     const f32x4* p = (const f32x4*)(rsp + (size_t)t * 64) + fq * n4; float s = 0.f;
;     for (int i = 0; i < n4; ++i) { const f32x4 v = p[i]; s += (v[0] + v[1]) + (v[2] + v[3]); }
;     s += __shfl_xor(s, 16); s += __shfl_xor(s, 32);
;     return rsqrtf(s * (1.0f / D) + EPS);
; }
;     __device__ __forceinline__ void operator()(const f32x4 (&acc)[2][2][4][2], const pg8::Unit& u, int wr, int wc, int fr, int fq) const {
;     ...
;                     const int t = rowb + ai * 128 + m * 16; const float rs = row_rstd(rsp, t, 2, fq);
;                     const int chunk = t >> 6, l = t & 63;
;                     bf16_t* vt = VT + ((size_t)(chunk * 8 + h) * 512 + eb) * 64 + l;
; #pragma unroll
;                     for (int bj = 0; bj < 2; ++bj)
; #pragma unroll
;                         for (int n = 0; n < 2; ++n)
; #pragma unroll
;                             for (int jj = 0; jj < 4; ++jj) vt[(bj * 128 + 4 * n + jj) * 64] = (bf16_t)f2bf(acc[ai][bj][m][n][jj] * rs);
	v_mov_b32_e32 v170, v140
	s_waitcnt vmcnt(0)
	v_mov_b32_e32 v171, v134
	v_mov_b32_e32 v134, v141
	v_mov_b32_e32 v140, v142
	v_mov_b32_e32 v141, v136
	v_mov_b32_e32 v136, v143
	v_pk_add_f32 v[134:135], v[170:171], v[134:135]
	v_pk_add_f32 v[136:137], v[140:141], v[136:137]
	s_nop 0
	v_pk_add_f32 v[134:135], v[134:135], v[136:137]
	s_nop 0
	v_add_f32_e32 v134, 0, v134
	v_add_f32_e32 v134, v134, v135
	ds_bpermute_b32 v135, v138, v134
	s_waitcnt lgkmcnt(0)
	v_add_f32_e32 v134, v134, v135
	ds_bpermute_b32 v135, v139, v134
	s_waitcnt lgkmcnt(0)
	v_add_f32_e32 v134, v134, v135
	v_fmamk_f32 v134, v134, 0x3a000000, v223
	v_cmp_gt_f32_e32 vcc, s97, v134
	v_mul_f32_e32 v135, 0x4b800000, v134
	s_nop 0
	v_cndmask_b32_e32 v134, v134, v135, vcc
	v_rsq_f32_e32 v134, v134
	s_nop 0
	v_mul_f32_e32 v135, 0x45800000, v134
	v_cndmask_b32_e32 v134, v134, v135, vcc
	v_mul_f32_e32 v135, v28, v134
	v_bfe_u32 v136, v135, 16, 1
	v_add3_u32 v135, v135, v136, s75
	global_store_short_d16_hi v[132:133], v135, off offset:64
	v_mul_f32_e32 v135, v29, v134
	v_bfe_u32 v136, v135, 16, 1
	v_add3_u32 v135, v135, v136, s75
	global_store_short_d16_hi v[132:133], v135, off offset:192
	v_mul_f32_e32 v135, v30, v134
	v_bfe_u32 v136, v135, 16, 1
	v_add3_u32 v135, v135, v136, s75
	global_store_short_d16_hi v[132:133], v135, off offset:320
	v_mul_f32_e32 v135, v31, v134
	v_bfe_u32 v136, v135, 16, 1
	v_add3_u32 v135, v135, v136, s75
	global_store_short_d16_hi v[132:133], v135, off offset:448
	v_mul_f32_e32 v135, v24, v134
	v_bfe_u32 v136, v135, 16, 1
	v_add3_u32 v135, v135, v136, s75
	global_store_short_d16_hi v[132:133], v135, off offset:576
	v_mul_f32_e32 v135, v25, v134
	v_bfe_u32 v136, v135, 16, 1
	v_add3_u32 v135, v135, v136, s75
	global_store_short_d16_hi v[132:133], v135, off offset:704
	v_mul_f32_e32 v135, v26, v134
	v_bfe_u32 v136, v135, 16, 1
	v_add3_u32 v135, v135, v136, s75
	global_store_short_d16_hi v[132:133], v135, off offset:832
	v_mul_f32_e32 v135, v27, v134
	v_bfe_u32 v136, v135, 16, 1
	v_add3_u32 v135, v135, v136, s75
	global_store_short_d16_hi v[132:133], v135, off offset:960
	v_mul_f32_e32 v135, v20, v134
	v_bfe_u32 v136, v135, 16, 1
	v_add3_u32 v135, v135, v136, s75
	global_store_short_d16_hi v[130:131], v135, off offset:64
	v_mul_f32_e32 v135, v21, v134
	v_bfe_u32 v136, v135, 16, 1
	v_add3_u32 v135, v135, v136, s75
	global_store_short_d16_hi v[130:131], v135, off offset:192
	v_mul_f32_e32 v135, v22, v134
	v_bfe_u32 v136, v135, 16, 1
	v_add3_u32 v135, v135, v136, s75
	global_store_short_d16_hi v[130:131], v135, off offset:320
	v_mul_f32_e32 v135, v23, v134
	v_bfe_u32 v136, v135, 16, 1
	v_add3_u32 v135, v135, v136, s75
	global_store_short_d16_hi v[130:131], v135, off offset:448
	v_mul_f32_e32 v135, v16, v134
	v_bfe_u32 v136, v135, 16, 1
	v_add3_u32 v135, v135, v136, s75
	global_store_short_d16_hi v[130:131], v135, off offset:576
	v_mul_f32_e32 v135, v17, v134
	v_bfe_u32 v136, v135, 16, 1
	v_add3_u32 v135, v135, v136, s75
	global_store_short_d16_hi v[130:131], v135, off offset:704
	v_mul_f32_e32 v135, v18, v134
	v_bfe_u32 v136, v135, 16, 1
	v_add3_u32 v135, v135, v136, s75
	v_mul_f32_e32 v134, v19, v134
	global_store_short_d16_hi v[130:131], v135, off offset:832
	v_bfe_u32 v135, v134, 16, 1
	v_add3_u32 v134, v134, v135, s75
	global_store_short_d16_hi v[130:131], v134, off offset:960
	v_lshl_add_u64 v[134:135], v[128:129], 0, s[4:5]
	s_mov_b32 s4, 0xb000
	v_add_co_u32_e32 v128, vcc, s4, v128
	s_nop 1
	v_addc_co_u32_e32 v129, vcc, 0, v129, vcc
	global_load_dwordx4 v[140:143], v[128:129], off
	s_nop 0
	global_load_dwordx4 v[134:137], v[134:135], off offset:16
	s_waitcnt vmcnt(1)
	v_mov_b32_e32 v128, v140
	s_waitcnt vmcnt(0)
	v_mov_b32_e32 v129, v134
	v_mov_b32_e32 v134, v141
	v_pk_add_f32 v[128:129], v[128:129], v[134:135]
	v_mov_b32_e32 v134, v142
	v_mov_b32_e32 v135, v136
	v_mov_b32_e32 v136, v143
	v_pk_add_f32 v[134:135], v[134:135], v[136:137]
	s_nop 0
	v_pk_add_f32 v[128:129], v[128:129], v[134:135]
	s_nop 0
	v_add_f32_e32 v128, 0, v128
	v_add_f32_e32 v128, v128, v129
	ds_bpermute_b32 v129, v138, v128
	s_waitcnt lgkmcnt(0)
	v_add_f32_e32 v128, v128, v129
	ds_bpermute_b32 v129, v139, v128
	s_waitcnt lgkmcnt(0)
	v_add_f32_e32 v128, v128, v129
	v_fmamk_f32 v128, v128, 0x3a000000, v223
	v_cmp_gt_f32_e32 vcc, s97, v128
	v_mul_f32_e32 v129, 0x4b800000, v128
	s_nop 0
	v_cndmask_b32_e32 v128, v128, v129, vcc
	v_rsq_f32_e32 v128, v128
	s_nop 0
	v_mul_f32_e32 v129, 0x45800000, v128
	v_cndmask_b32_e32 v128, v128, v129, vcc
	v_mul_f32_e32 v129, v12, v128
	v_bfe_u32 v134, v129, 16, 1
	v_add3_u32 v129, v129, v134, s75
	global_store_short_d16_hi v[132:133], v129, off offset:96
	v_mul_f32_e32 v129, v13, v128
	v_bfe_u32 v134, v129, 16, 1
	v_add3_u32 v129, v129, v134, s75
	global_store_short_d16_hi v[132:133], v129, off offset:224
	v_mul_f32_e32 v129, v14, v128
	v_bfe_u32 v134, v129, 16, 1
	v_add3_u32 v129, v129, v134, s75
	global_store_short_d16_hi v[132:133], v129, off offset:352
	v_mul_f32_e32 v129, v15, v128
	v_bfe_u32 v134, v129, 16, 1
	v_add3_u32 v129, v129, v134, s75
	global_store_short_d16_hi v[132:133], v129, off offset:480
	v_mul_f32_e32 v129, v8, v128
	v_bfe_u32 v134, v129, 16, 1
	v_add3_u32 v129, v129, v134, s75
	global_store_short_d16_hi v[132:133], v129, off offset:608
	v_mul_f32_e32 v129, v9, v128
	v_bfe_u32 v134, v129, 16, 1
	v_add3_u32 v129, v129, v134, s75
	global_store_short_d16_hi v[132:133], v129, off offset:736
	v_mul_f32_e32 v129, v10, v128
	v_bfe_u32 v134, v129, 16, 1
	v_add3_u32 v129, v129, v134, s75
	global_store_short_d16_hi v[132:133], v129, off offset:864
	v_mul_f32_e32 v129, v11, v128
	v_bfe_u32 v134, v129, 16, 1
	v_add3_u32 v129, v129, v134, s75
	global_store_short_d16_hi v[132:133], v129, off offset:992
	v_mul_f32_e32 v129, v4, v128
	v_bfe_u32 v132, v129, 16, 1
	v_add3_u32 v129, v129, v132, s75
	global_store_short_d16_hi v[130:131], v129, off offset:96
	v_mul_f32_e32 v129, v5, v128
	v_bfe_u32 v132, v129, 16, 1
	v_add3_u32 v129, v129, v132, s75
	global_store_short_d16_hi v[130:131], v129, off offset:224
	v_mul_f32_e32 v129, v6, v128
	v_bfe_u32 v132, v129, 16, 1
	v_add3_u32 v129, v129, v132, s75
	global_store_short_d16_hi v[130:131], v129, off offset:352
	v_mul_f32_e32 v129, v7, v128
	v_bfe_u32 v132, v129, 16, 1
	v_add3_u32 v129, v129, v132, s75
	global_store_short_d16_hi v[130:131], v129, off offset:480
	v_mul_f32_e32 v129, v0, v128
	v_bfe_u32 v132, v129, 16, 1
	v_add3_u32 v129, v129, v132, s75
	global_store_short_d16_hi v[130:131], v129, off offset:608
	v_mul_f32_e32 v129, v1, v128
	v_bfe_u32 v132, v129, 16, 1
	v_add3_u32 v129, v129, v132, s75
	global_store_short_d16_hi v[130:131], v129, off offset:736
	v_mul_f32_e32 v129, v2, v128
	v_bfe_u32 v132, v129, 16, 1
	v_add3_u32 v129, v129, v132, s75
	v_mul_f32_e32 v128, v3, v128
	global_store_short_d16_hi v[130:131], v129, off offset:864
	v_bfe_u32 v129, v128, 16, 1
	v_add3_u32 v128, v128, v129, s75
	global_store_short_d16_hi v[130:131], v128, off offset:992
